# grid barrier: non-leader workgroups wait on the global generation word directly (no per-XCD republish level); leader release / per-workgroup acquire unchanged
# speedup vs baseline: 1.0102x; 1.0026x over previous
.LBB0_71:
	s_or_b64 exec, exec, s[10:11]
	v_cvt_f32_u32_e32 v4, v2
	s_waitcnt vmcnt(0)
	v_readfirstlane_b32 s8, v3
	v_sub_u32_e32 v3, 0, v2
	v_rcp_iflag_f32_e32 v4, v4
	v_add_u32_e32 v5, s8, v1
	v_mul_f32_e32 v4, 0x4f7ffffe, v4
	v_cvt_u32_f32_e32 v4, v4
	v_mul_lo_u32 v1, v3, v4
	v_mul_hi_u32 v1, v4, v1
	v_add_u32_e32 v1, v4, v1
	v_mul_hi_u32 v1, v5, v1
	v_mul_lo_u32 v3, v1, v2
	v_sub_u32_e32 v3, v5, v3
	v_add_u32_e32 v4, 1, v1
	v_cmp_ge_u32_e32 vcc, v3, v2
	s_nop 1
	v_cndmask_b32_e32 v1, v1, v4, vcc
	v_sub_u32_e32 v4, v3, v2
	v_cndmask_b32_e32 v3, v3, v4, vcc
	v_add_u32_e32 v4, 1, v1
	v_cmp_ge_u32_e32 vcc, v3, v2
	v_add_u32_e32 v3, 1, v5
	s_nop 0
	v_cndmask_b32_e32 v1, v1, v4, vcc
	v_mul_lo_u32 v4, v2, v1
	v_add_u32_e32 v2, v4, v2
	v_cmp_ne_u32_e32 vcc, v3, v2
	s_and_saveexec_b64 s[8:9], vcc
	s_xor_b64 s[8:9], exec, s[8:9]
	s_cbranch_execz .LBB0_85
	s_waitcnt lgkmcnt(0)
	v_mov_b32_e32 v0, 0x2000
	s_add_u32 s14, s4, 0x2f81500
	s_addc_u32 s15, s5, 0
	v_mov_b32_e32 v0, 0
	global_load_dword v0, v0, s[14:15] sc1
	s_waitcnt vmcnt(0)
	v_cmp_eq_u32_e32 vcc, v0, v1
	s_and_saveexec_b64 s[10:11], vcc
	s_cbranch_execz .LBB0_84
	s_add_u32 s12, s4, 0x2f7e200
	s_addc_u32 s13, s5, 0
	s_mov_b32 s26, 1
	s_mov_b64 s[16:17], 0
	v_mov_b32_e32 v0, 0
	s_branch .LBB0_75

.LBB0_102:
	s_or_b64 exec, exec, s[4:5]
	s_mov_b64 s[4:5], exec
	v_mbcnt_lo_u32_b32 v0, s4, 0
	v_mbcnt_hi_u32_b32 v0, s5, v0
	v_cmp_eq_u32_e32 vcc, 0, v0
	s_waitcnt vmcnt(0)
	buffer_inv sc1
	s_and_saveexec_b64 s[8:9], vcc
	s_cbranch_execz .LBB0_104
	s_bcnt1_i32_b64 s4, s[4:5]
	v_mov_b32_e32 v0, 0x2000
	v_mov_b32_e32 v1, s4
.LBB0_104:
	s_or_b64 exec, exec, s[8:9]
	s_waitcnt vmcnt(0)

.LBB0_177:
	s_or_b64 exec, exec, s[8:9]
	v_cvt_f32_u32_e32 v4, v2
	s_waitcnt vmcnt(0)
	v_readfirstlane_b32 s6, v3
	v_sub_u32_e32 v3, 0, v2
	v_rcp_iflag_f32_e32 v4, v4
	v_add_u32_e32 v5, s6, v1
	v_mul_f32_e32 v4, 0x4f7ffffe, v4
	v_cvt_u32_f32_e32 v4, v4
	v_mul_lo_u32 v1, v3, v4
	v_mul_hi_u32 v1, v4, v1
	v_add_u32_e32 v1, v4, v1
	v_mul_hi_u32 v1, v5, v1
	v_mul_lo_u32 v3, v1, v2
	v_sub_u32_e32 v3, v5, v3
	v_add_u32_e32 v4, 1, v1
	v_cmp_ge_u32_e32 vcc, v3, v2
	s_nop 1
	v_cndmask_b32_e32 v1, v1, v4, vcc
	v_sub_u32_e32 v4, v3, v2
	v_cndmask_b32_e32 v3, v3, v4, vcc
	v_add_u32_e32 v4, 1, v1
	v_cmp_ge_u32_e32 vcc, v3, v2
	v_add_u32_e32 v3, 1, v5
	s_nop 0
	v_cndmask_b32_e32 v1, v1, v4, vcc
	v_mul_lo_u32 v4, v2, v1
	v_add_u32_e32 v2, v4, v2
	v_cmp_ne_u32_e32 vcc, v3, v2
	s_and_saveexec_b64 s[6:7], vcc
	s_xor_b64 s[6:7], exec, s[6:7]
	s_cbranch_execz .LBB0_191
	s_waitcnt lgkmcnt(0)
	s_add_u32 s12, s2, 0x2f81500
	s_addc_u32 s13, s3, 0
	v_mov_b32_e32 v0, 0
	global_load_dword v0, v0, s[12:13] sc1
	s_waitcnt vmcnt(0)
	v_cmp_eq_u32_e32 vcc, v0, v1
	s_and_saveexec_b64 s[8:9], vcc
	s_cbranch_execz .LBB0_190
	s_add_u32 s10, s2, 0x2f7e200
	s_addc_u32 s11, s3, 0
	s_mov_b32 s24, 1
	s_mov_b64 s[14:15], 0
	s_branch .LBB0_181

.LBB0_208:
	s_or_b64 exec, exec, s[2:3]
	s_mov_b64 s[2:3], exec
	v_mbcnt_lo_u32_b32 v0, s2, 0
	v_mbcnt_hi_u32_b32 v0, s3, v0
	v_cmp_eq_u32_e32 vcc, 0, v0
	s_waitcnt vmcnt(0)
	buffer_inv sc1
	s_and_saveexec_b64 s[6:7], vcc
	s_cbranch_execz .LBB0_210
	s_bcnt1_i32_b64 s2, s[2:3]
	v_mov_b32_e32 v0, s2
.LBB0_210:
	s_or_b64 exec, exec, s[6:7]
	s_waitcnt vmcnt(0)

.LBB0_237:
	s_or_b64 exec, exec, s[10:11]
	v_cvt_f32_u32_e32 v4, v2
	s_waitcnt vmcnt(0)
	v_readfirstlane_b32 s8, v3
	v_sub_u32_e32 v3, 0, v2
	v_rcp_iflag_f32_e32 v4, v4
	v_add_u32_e32 v5, s8, v1
	v_mul_f32_e32 v4, 0x4f7ffffe, v4
	v_cvt_u32_f32_e32 v4, v4
	v_mul_lo_u32 v1, v3, v4
	v_mul_hi_u32 v1, v4, v1
	v_add_u32_e32 v1, v4, v1
	v_mul_hi_u32 v1, v5, v1
	v_mul_lo_u32 v3, v1, v2
	v_sub_u32_e32 v3, v5, v3
	v_add_u32_e32 v4, 1, v1
	v_cmp_ge_u32_e32 vcc, v3, v2
	s_nop 1
	v_cndmask_b32_e32 v1, v1, v4, vcc
	v_sub_u32_e32 v4, v3, v2
	v_cndmask_b32_e32 v3, v3, v4, vcc
	v_add_u32_e32 v4, 1, v1
	v_cmp_ge_u32_e32 vcc, v3, v2
	v_add_u32_e32 v3, 1, v5
	s_nop 0
	v_cndmask_b32_e32 v1, v1, v4, vcc
	v_mul_lo_u32 v4, v2, v1
	v_add_u32_e32 v2, v4, v2
	v_cmp_ne_u32_e32 vcc, v3, v2
	s_and_saveexec_b64 s[8:9], vcc
	s_xor_b64 s[8:9], exec, s[8:9]
	s_cbranch_execz .LBB0_251
	s_waitcnt lgkmcnt(0)
	s_add_u32 s14, s2, 0x2f81500
	s_addc_u32 s15, s3, 0
	v_mov_b32_e32 v0, 0
	global_load_dword v0, v0, s[14:15] sc1
	s_waitcnt vmcnt(0)
	v_cmp_eq_u32_e32 vcc, v0, v1
	s_and_saveexec_b64 s[10:11], vcc
	s_cbranch_execz .LBB0_250
	s_add_u32 s12, s2, 0x2f7e200
	s_addc_u32 s13, s3, 0
	s_mov_b32 s26, 1
	s_mov_b64 s[16:17], 0
	s_branch .LBB0_241

.LBB0_268:
	s_or_b64 exec, exec, s[2:3]
	s_mov_b64 s[2:3], exec
	v_mbcnt_lo_u32_b32 v0, s2, 0
	v_mbcnt_hi_u32_b32 v0, s3, v0
	v_cmp_eq_u32_e32 vcc, 0, v0
	s_waitcnt vmcnt(0)
	buffer_inv sc1
	s_and_saveexec_b64 s[8:9], vcc
	s_cbranch_execz .LBB0_270
	s_bcnt1_i32_b64 s2, s[2:3]
	v_mov_b32_e32 v0, s2
.LBB0_270:
	s_or_b64 exec, exec, s[8:9]
	s_waitcnt vmcnt(0)

.LBB0_340:
	s_or_b64 exec, exec, s[2:3]
	s_mov_b64 s[2:3], exec
	v_mbcnt_lo_u32_b32 v0, s2, 0
	v_mbcnt_hi_u32_b32 v0, s3, v0
	v_cmp_eq_u32_e32 vcc, 0, v0
	s_waitcnt vmcnt(0)
	buffer_inv sc1
	s_and_saveexec_b64 s[6:7], vcc
	s_cbranch_execz .LBB0_342
	s_bcnt1_i32_b64 s2, s[2:3]
	v_mov_b32_e32 v0, s2
.LBB0_342:
	s_or_b64 exec, exec, s[6:7]
	s_waitcnt vmcnt(0)

.LBB0_580:
	s_or_b64 exec, exec, s[2:3]
	s_mov_b64 s[2:3], exec
	v_mbcnt_lo_u32_b32 v0, s2, 0
	v_mbcnt_hi_u32_b32 v0, s3, v0
	v_cmp_eq_u32_e32 vcc, 0, v0
	s_waitcnt vmcnt(0)
	buffer_inv sc1
	s_and_saveexec_b64 s[6:7], vcc
	s_cbranch_execz .LBB0_582
	s_bcnt1_i32_b64 s2, s[2:3]
	v_mov_b32_e32 v0, s2
.LBB0_582:
	s_or_b64 exec, exec, s[6:7]
	s_waitcnt vmcnt(0)

.LBB0_658:
	s_or_b64 exec, exec, s[2:3]
	s_mov_b64 s[2:3], exec
	v_mbcnt_lo_u32_b32 v0, s2, 0
	v_mbcnt_hi_u32_b32 v0, s3, v0
	v_cmp_eq_u32_e32 vcc, 0, v0
	s_waitcnt vmcnt(0)
	buffer_inv sc1
	s_and_saveexec_b64 s[6:7], vcc
	s_cbranch_execz .LBB0_660
	s_bcnt1_i32_b64 s2, s[2:3]
	v_mov_b32_e32 v0, s2
.LBB0_660:
	s_or_b64 exec, exec, s[6:7]
	s_waitcnt vmcnt(0)

.LBB0_848:
	s_or_b64 exec, exec, s[2:3]
	s_mov_b64 s[2:3], exec
	v_mbcnt_lo_u32_b32 v0, s2, 0
	v_mbcnt_hi_u32_b32 v0, s3, v0
	v_cmp_eq_u32_e32 vcc, 0, v0
	s_waitcnt vmcnt(0)
	buffer_inv sc1
	s_and_saveexec_b64 s[6:7], vcc
	s_cbranch_execz .LBB0_850
	s_bcnt1_i32_b64 s2, s[2:3]
	v_mov_b32_e32 v0, s2
.LBB0_850:
	s_or_b64 exec, exec, s[6:7]
	s_waitcnt vmcnt(0)

.LBB0_1014:
	s_or_b64 exec, exec, s[2:3]
	s_mov_b64 s[2:3], exec
	v_mbcnt_lo_u32_b32 v0, s2, 0
	v_mbcnt_hi_u32_b32 v0, s3, v0
	v_cmp_eq_u32_e32 vcc, 0, v0
	s_waitcnt vmcnt(0)
	buffer_inv sc1
	s_and_saveexec_b64 s[8:9], vcc
	s_cbranch_execz .LBB0_1016
	s_bcnt1_i32_b64 s2, s[2:3]
	v_mov_b32_e32 v0, s2
.LBB0_1016:
	s_or_b64 exec, exec, s[8:9]
	s_waitcnt vmcnt(0)

.LBB0_1243:
	s_or_b64 exec, exec, s[2:3]
	s_mov_b64 s[2:3], exec
	v_mbcnt_lo_u32_b32 v0, s2, 0
	v_mbcnt_hi_u32_b32 v0, s3, v0
	v_cmp_eq_u32_e32 vcc, 0, v0
	s_waitcnt vmcnt(0)
	buffer_inv sc1
	s_and_saveexec_b64 s[6:7], vcc
	s_cbranch_execz .Ltr_LBB0_107
	s_bcnt1_i32_b64 s2, s[2:3]
	v_mov_b32_e32 v0, s2
	s_branch .Ltr_LBB0_107
